# norm phases: the 4 row loads of the FFN-norm loop issued together (were 4 serialized HBM round trips per row); final-norm gamma loads hoisted out of the row loop
# speedup vs baseline: 1.0004x; 1.0004x over previous
.LBB0_858:
	v_add_co_u32_e32 v14, vcc, 0xfb800000, v6
	v_min_i32_e32 v22, 0x4000, v28
	s_nop 0
	v_addc_co_u32_e32 v15, vcc, -1, v7, vcc
	global_load_dwordx4 v[160:163], v[14:15], off offset:-3072
	global_load_dwordx4 v[164:167], v[14:15], off offset:-2048
	global_load_dwordx4 v[168:171], v[14:15], off offset:-1024
	global_load_dwordx4 v[18:21], v[14:15], off
	v_ashrrev_i32_e32 v22, 11, v22
	s_mov_b64 s[18:19], 0x6000
	v_add_u32_e32 v28, s96, v28
	s_waitcnt vmcnt(3)
	v_lshlrev_b32_e32 v60, 16, v160
	v_and_b32_e32 v59, 0xffff0000, v160
	v_lshlrev_b32_e32 v58, 16, v161
	v_and_b32_e32 v57, 0xffff0000, v161
	v_lshlrev_b32_e32 v56, 16, v162
	v_and_b32_e32 v55, 0xffff0000, v162
	v_lshlrev_b32_e32 v54, 16, v163
	v_and_b32_e32 v9, 0xffff0000, v163
	v_mul_f32_e32 v23, v59, v59
	v_fmac_f32_e32 v23, v60, v60
	v_fmac_f32_e32 v23, v58, v58
	v_fmac_f32_e32 v23, v57, v57
	v_fmac_f32_e32 v23, v56, v56
	v_fmac_f32_e32 v23, v55, v55
	v_fmac_f32_e32 v23, v54, v54
	v_fmac_f32_e32 v23, v9, v9
	s_waitcnt vmcnt(2)
	v_lshlrev_b32_e32 v53, 16, v164
	v_and_b32_e32 v52, 0xffff0000, v164
	v_lshlrev_b32_e32 v51, 16, v165
	v_and_b32_e32 v50, 0xffff0000, v165
	v_lshlrev_b32_e32 v49, 16, v166
	v_and_b32_e32 v48, 0xffff0000, v166
	v_lshlrev_b32_e32 v47, 16, v167
	v_and_b32_e32 v11, 0xffff0000, v167
	v_fmac_f32_e32 v23, v53, v53
	v_fmac_f32_e32 v23, v52, v52
	v_fmac_f32_e32 v23, v51, v51
	v_fmac_f32_e32 v23, v50, v50
	v_fmac_f32_e32 v23, v49, v49
	v_fmac_f32_e32 v23, v48, v48
	v_fmac_f32_e32 v23, v47, v47
	v_fmac_f32_e32 v23, v11, v11
	s_waitcnt vmcnt(1)
	v_lshlrev_b32_e32 v46, 16, v168
	v_and_b32_e32 v45, 0xffff0000, v168
	v_lshlrev_b32_e32 v44, 16, v169
	v_and_b32_e32 v43, 0xffff0000, v169
	v_lshlrev_b32_e32 v42, 16, v170
	v_and_b32_e32 v41, 0xffff0000, v170
	v_lshlrev_b32_e32 v40, 16, v171
	v_and_b32_e32 v13, 0xffff0000, v171
	v_fmac_f32_e32 v23, v46, v46
	v_fmac_f32_e32 v23, v45, v45
	v_fmac_f32_e32 v23, v44, v44
	v_fmac_f32_e32 v23, v43, v43
	v_fmac_f32_e32 v23, v42, v42
	v_fmac_f32_e32 v23, v41, v41
	v_fmac_f32_e32 v23, v40, v40
	v_fmac_f32_e32 v23, v13, v13
	s_waitcnt vmcnt(0)
	v_lshlrev_b32_e32 v38, 16, v18
	v_and_b32_e32 v37, 0xffff0000, v18
	v_fmac_f32_e32 v23, v38, v38
	v_lshlrev_b32_e32 v36, 16, v19
	v_fmac_f32_e32 v23, v37, v37
	v_and_b32_e32 v35, 0xffff0000, v19
	v_fmac_f32_e32 v23, v36, v36
	v_and_b32_e32 v18, 0xffff0000, v20
	v_lshlrev_b32_e32 v19, 16, v20
	v_fmac_f32_e32 v23, v35, v35
	v_pk_mul_f32 v[14:15], v[18:19], v[18:19]
	s_nop 0
	v_add_f32_e32 v15, v15, v23
	v_add_f32_e32 v23, v14, v15
	v_and_b32_e32 v14, 0xffff0000, v21
	v_lshlrev_b32_e32 v15, 16, v21
	v_pk_mul_f32 v[20:21], v[14:15], v[14:15]
	s_nop 0
	v_add_f32_e32 v21, v21, v23
	v_add_f32_e32 v20, v20, v21
	ds_bpermute_b32 v21, v29, v20
	s_waitcnt lgkmcnt(0)
	v_add_f32_e32 v20, v20, v21
	ds_bpermute_b32 v21, v30, v20
	s_waitcnt lgkmcnt(0)
	v_add_f32_e32 v20, v20, v21
	ds_bpermute_b32 v21, v31, v20
	s_waitcnt lgkmcnt(0)
	v_add_f32_e32 v20, v20, v21
	ds_bpermute_b32 v21, v32, v20
	s_waitcnt lgkmcnt(0)
	v_add_f32_e32 v20, v20, v21
	ds_bpermute_b32 v21, v33, v20
	s_waitcnt lgkmcnt(0)
	v_add_f32_e32 v20, v20, v21
	ds_bpermute_b32 v21, v34, v20
	s_waitcnt lgkmcnt(0)
	v_add_f32_e32 v20, v20, v21
	v_fmamk_f32 v20, v20, 0x3a000000, v209
	v_cmp_gt_f32_e32 vcc, s55, v20
	v_mul_f32_e32 v21, 0x4b800000, v20
	s_nop 0
	v_cndmask_b32_e32 v20, v20, v21, vcc
	v_rsq_f32_e32 v20, v20
	s_nop 0
	v_mul_f32_e32 v21, 0x45800000, v20
	v_cndmask_b32_e32 v39, v20, v21, vcc
	v_mul_hi_i32_i24_e32 v21, 0xc000, v22
	v_mul_i32_i24_e32 v20, 0xc000, v22
	v_lshl_add_u64 v[22:23], s[90:91], 0, v[20:21]
	v_lshl_add_u64 v[20:21], v[22:23], 0, s[18:19]
	s_mov_b64 s[18:19], 0x8000
	v_lshl_add_u64 v[22:23], v[22:23], 0, s[18:19]
	v_lshl_add_u64 v[26:27], v[22:23], 0, v[16:17]
	v_lshl_add_u64 v[24:25], v[20:21], 0, v[16:17]
	global_load_dwordx4 v[62:65], v[0:1], off offset:16
	global_load_dwordx4 v[66:69], v[0:1], off
	global_load_dwordx4 v[70:73], v[26:27], off offset:16
	global_load_dwordx4 v[74:77], v[26:27], off
	global_load_dwordx4 v[78:81], v[24:25], off offset:16
	s_nop 0
	global_load_dwordx4 v[24:27], v[24:25], off
	v_mul_f32_e32 v60, v39, v60
	v_mul_f32_e32 v59, v39, v59
	v_mul_f32_e32 v58, v39, v58
	v_mul_f32_e32 v57, v39, v57
	v_mul_f32_e32 v56, v39, v56
	v_mul_f32_e32 v55, v39, v55
	v_mul_f32_e32 v54, v39, v54
	v_mul_f32_e32 v9, v39, v9
	v_mul_f32_e32 v49, v39, v49
	v_mul_f32_e32 v52, v39, v52
	v_mul_f32_e32 v51, v39, v51
	v_mul_f32_e32 v11, v39, v11
	v_mul_f32_e32 v50, v39, v50
	v_mul_f32_e32 v42, v39, v42
	v_mul_f32_e32 v44, v39, v44
	v_mul_f32_e32 v13, v39, v13
	v_mul_f32_e32 v43, v39, v43
	v_mul_f32_e32 v19, v39, v19
	v_mul_f32_e32 v18, v39, v18
	v_mul_f32_e32 v15, v39, v15
	v_mul_f32_e32 v14, v39, v14
	v_cmp_le_i32_e32 vcc, s57, v28
	s_or_b64 s[14:15], vcc, s[14:15]
	s_waitcnt vmcnt(5)
	v_mul_f32_e32 v56, v62, v56
	s_waitcnt vmcnt(4)
	v_mul_f32_e32 v60, v66, v60
	v_mul_f32_e32 v59, v67, v59
	s_waitcnt vmcnt(2)
	v_add_f32_e32 v61, 1.0, v74
	v_mul_f32_e32 v58, v68, v58
	s_waitcnt vmcnt(0)
	v_fma_f32 v24, v61, v60, v24
	v_add_f32_e32 v60, 1.0, v75
	v_fma_f32 v25, v60, v59, v25
	v_add_f32_e32 v59, 1.0, v76
	v_fma_f32 v26, v59, v58, v26
	v_mul_f32_e32 v57, v69, v57
	v_add_f32_e32 v58, 1.0, v77
	v_fmac_f32_e32 v27, v58, v57
	v_add_f32_e32 v57, 1.0, v70
	v_fma_f32 v56, v57, v56, v78
	v_mul_f32_e32 v55, v63, v55
	v_add_f32_e32 v57, 1.0, v71
	v_fma_f32 v55, v57, v55, v79
	v_mul_f32_e32 v54, v64, v54
	v_add_f32_e32 v57, 1.0, v72
	v_fma_f32 v54, v57, v54, v80
	v_mul_f32_e32 v9, v65, v9
	v_add_f32_e32 v57, 1.0, v73
	v_fmac_f32_e32 v81, v57, v9
	v_mov_b32_e32 v9, v17
	v_cvt_pk_bf16_f32 v24, v24, v25
	v_cvt_pk_bf16_f32 v25, v26, v27
	v_cvt_pk_bf16_f32 v26, v56, v55
	v_cvt_pk_bf16_f32 v27, v54, v81
	global_store_dwordx4 v[6:7], v[24:27], off offset:-3072
	v_lshl_add_u64 v[62:63], v[22:23], 0, v[8:9]
	v_lshl_add_u64 v[70:71], v[20:21], 0, v[8:9]
	global_load_dwordx4 v[24:27], v[0:1], off offset:2064
	global_load_dwordx4 v[54:57], v[0:1], off offset:2048
	global_load_dwordx4 v[58:61], v[62:63], off offset:16
	s_nop 0
	global_load_dwordx4 v[62:65], v[62:63], off
	s_nop 0
	global_load_dwordx4 v[66:69], v[70:71], off offset:16
	s_nop 0
	global_load_dwordx4 v[70:73], v[70:71], off
	v_mul_f32_e32 v9, v39, v53
	s_waitcnt vmcnt(5)
	v_mul_f32_e32 v24, v24, v49
	s_waitcnt vmcnt(4)
	v_mul_f32_e32 v9, v54, v9
	s_waitcnt vmcnt(3)
	v_add_f32_e32 v49, 1.0, v58
	s_waitcnt vmcnt(2)
	v_add_f32_e32 v53, 1.0, v62
	s_waitcnt vmcnt(1)
	v_fma_f32 v49, v49, v24, v66
	v_mul_f32_e32 v24, v39, v48
	v_mul_f32_e32 v24, v25, v24
	v_add_f32_e32 v25, 1.0, v59
	v_fma_f32 v48, v25, v24, v67
	v_mul_f32_e32 v24, v39, v47
	s_waitcnt vmcnt(0)
	v_fma_f32 v9, v53, v9, v70
	v_mul_f32_e32 v52, v55, v52
	v_add_f32_e32 v53, 1.0, v63
	v_mul_f32_e32 v24, v26, v24
	v_add_f32_e32 v25, 1.0, v60
	v_fma_f32 v52, v53, v52, v71
	v_mul_f32_e32 v51, v56, v51
	v_add_f32_e32 v53, 1.0, v64
	v_fma_f32 v47, v25, v24, v68
	v_mul_f32_e32 v11, v27, v11
	v_add_f32_e32 v24, 1.0, v61
	v_fma_f32 v51, v53, v51, v72
	v_mul_f32_e32 v50, v57, v50
	v_add_f32_e32 v53, 1.0, v65
	v_fmac_f32_e32 v69, v24, v11
	v_mov_b32_e32 v11, v17
	v_fmac_f32_e32 v73, v53, v50
	v_cvt_pk_bf16_f32 v24, v9, v52
	v_cvt_pk_bf16_f32 v25, v51, v73
	v_cvt_pk_bf16_f32 v26, v49, v48
	v_cvt_pk_bf16_f32 v27, v47, v69
	global_store_dwordx4 v[6:7], v[24:27], off offset:-2048
	v_lshl_add_u64 v[56:57], v[22:23], 0, v[10:11]
	v_lshl_add_u64 v[64:65], v[20:21], 0, v[10:11]
	global_load_dwordx4 v[24:27], v[2:3], off offset:16
	global_load_dwordx4 v[48:51], v[2:3], off
	global_load_dwordx4 v[52:55], v[56:57], off offset:16
	s_nop 0
	global_load_dwordx4 v[56:59], v[56:57], off
	s_nop 0
	global_load_dwordx4 v[60:63], v[64:65], off offset:16
	s_nop 0
	global_load_dwordx4 v[64:67], v[64:65], off
	v_mul_f32_e32 v9, v39, v46
	s_waitcnt vmcnt(5)
	v_mul_f32_e32 v24, v24, v42
	s_waitcnt vmcnt(4)
	v_mul_f32_e32 v9, v48, v9
	s_waitcnt vmcnt(3)
	v_add_f32_e32 v42, 1.0, v52
	s_waitcnt vmcnt(2)
	v_add_f32_e32 v11, 1.0, v56
	s_waitcnt vmcnt(1)
	v_fma_f32 v42, v42, v24, v60
	v_mul_f32_e32 v24, v39, v41
	v_mul_f32_e32 v24, v25, v24
	v_add_f32_e32 v25, 1.0, v53
	s_waitcnt vmcnt(0)
	v_fma_f32 v9, v11, v9, v64
	v_mul_f32_e32 v11, v39, v45
	v_fma_f32 v41, v25, v24, v61
	v_mul_f32_e32 v24, v39, v40
	v_mul_f32_e32 v11, v49, v11
	v_add_f32_e32 v45, 1.0, v57
	v_mul_f32_e32 v24, v26, v24
	v_add_f32_e32 v25, 1.0, v54
	v_fma_f32 v11, v45, v11, v65
	v_mul_f32_e32 v44, v50, v44
	v_add_f32_e32 v45, 1.0, v58
	v_fma_f32 v40, v25, v24, v62
	v_mul_f32_e32 v13, v27, v13
	v_add_f32_e32 v24, 1.0, v55
	v_fma_f32 v44, v45, v44, v66
	v_mul_f32_e32 v43, v51, v43
	v_add_f32_e32 v45, 1.0, v59
	v_fmac_f32_e32 v63, v24, v13
	v_mov_b32_e32 v13, v17
	v_fmac_f32_e32 v67, v45, v43
	v_cvt_pk_bf16_f32 v24, v9, v11
	v_cvt_pk_bf16_f32 v25, v44, v67
	v_cvt_pk_bf16_f32 v26, v42, v41
	v_cvt_pk_bf16_f32 v27, v40, v63
	global_store_dwordx4 v[6:7], v[24:27], off offset:-1024
	v_lshl_add_u64 v[44:45], v[22:23], 0, v[12:13]
	v_lshl_add_u64 v[52:53], v[20:21], 0, v[12:13]
	global_load_dwordx4 v[20:23], v[4:5], off offset:16
	global_load_dwordx4 v[24:27], v[4:5], off
	global_load_dwordx4 v[40:43], v[44:45], off offset:16
	s_nop 0
	global_load_dwordx4 v[44:47], v[44:45], off
	s_nop 0
	global_load_dwordx4 v[48:51], v[52:53], off offset:16
	s_nop 0
	global_load_dwordx4 v[52:55], v[52:53], off
	v_mul_f32_e32 v9, v39, v38
	s_waitcnt vmcnt(5)
	v_mul_f32_e32 v19, v20, v19
	s_waitcnt vmcnt(4)
	v_mul_f32_e32 v9, v24, v9
	s_waitcnt vmcnt(3)
	v_add_f32_e32 v20, 1.0, v40
	s_waitcnt vmcnt(2)
	v_add_f32_e32 v11, 1.0, v44
	v_add_f32_e32 v13, 1.0, v45
	s_waitcnt vmcnt(0)
	v_fma_f32 v9, v11, v9, v52
	v_mul_f32_e32 v11, v39, v37
	v_mul_f32_e32 v11, v25, v11
	v_fma_f32 v11, v13, v11, v53
	v_mul_f32_e32 v13, v39, v36
	v_mul_f32_e32 v13, v26, v13
	v_add_f32_e32 v24, 1.0, v46
	v_fma_f32 v20, v20, v19, v48
	v_mul_f32_e32 v18, v21, v18
	v_add_f32_e32 v19, 1.0, v41
	v_fma_f32 v13, v24, v13, v54
	v_mul_f32_e32 v24, v39, v35
	v_fma_f32 v21, v19, v18, v49
	v_mul_f32_e32 v15, v22, v15
	v_add_f32_e32 v18, 1.0, v42
	v_mul_f32_e32 v24, v27, v24
	v_add_f32_e32 v25, 1.0, v47
	v_fma_f32 v15, v18, v15, v50
	v_mul_f32_e32 v14, v23, v14
	v_add_f32_e32 v18, 1.0, v43
	v_fmac_f32_e32 v55, v25, v24
	v_fmac_f32_e32 v51, v18, v14
	v_cvt_pk_bf16_f32 v18, v9, v11
	v_cvt_pk_bf16_f32 v19, v13, v55
	v_cvt_pk_bf16_f32 v20, v20, v21
	v_cvt_pk_bf16_f32 v21, v15, v51
	global_store_dwordx4 v[6:7], v[18:21], off
	v_lshl_add_u64 v[6:7], v[6:7], 0, s[26:27]
	s_andn2_b64 exec, exec, s[14:15]
	s_cbranch_execnz .LBB0_858

.LBB0_1052:
	v_readlane_b32 s8, v255, 8
	v_readlane_b32 s9, v255, 9
	s_mov_b64 s[4:5], s[8:9]
	s_lshl_b32 s0, s2, 3
	v_ashrrev_i32_e32 v6, 6, v208
	v_add_u32_e32 v10, s0, v6
	s_movk_i32 s1, 0x4000
	v_cmp_gt_i32_e32 vcc, s1, v10
	s_and_saveexec_b64 s[2:3], vcc
	v_readlane_b32 s10, v255, 31
	v_readlane_b32 s12, v255, 33
	v_readlane_b32 s11, v255, 32
	v_readlane_b32 s13, v255, 34
	s_cbranch_execz .LBB0_1055
	v_cmp_lt_i32_e32 vcc, v219, v212
	s_load_dwordx2 s[2:3], s[4:5], 0x40
	s_load_dwordx2 s[6:7], s[8:9], 0xe8
	v_cndmask_b32_e32 v0, v211, v219, vcc
	v_cmp_lt_i32_e32 vcc, v218, v212
	v_lshlrev_b32_e32 v11, 2, v0
	v_ashrrev_i32_e32 v7, 31, v6
	v_cndmask_b32_e32 v0, v211, v218, vcc
	v_lshlrev_b32_e32 v12, 2, v0
	v_xor_b32_e32 v0, 8, v211
	v_cmp_lt_i32_e32 vcc, v0, v212
	s_ashr_i32 s1, s0, 31
	v_lshl_add_u64 v[8:9], v[6:7], 0, s[0:1]
	v_cndmask_b32_e32 v0, v211, v0, vcc
	v_cmp_lt_i32_e32 vcc, v220, v212
	v_lshlrev_b32_e32 v13, 2, v0
	v_lshlrev_b64 v[6:7], 12, v[8:9]
	v_cndmask_b32_e32 v0, v211, v220, vcc
	v_cmp_lt_i32_e32 vcc, v215, v212
	v_lshlrev_b32_e32 v14, 2, v0
	v_and_b32_e32 v17, 63, v208
	v_cndmask_b32_e32 v0, v211, v215, vcc
	v_cmp_lt_i32_e32 vcc, v214, v212
	v_lshlrev_b32_e32 v15, 2, v0
	v_readlane_b32 s0, v254, 0
	v_cndmask_b32_e32 v0, v211, v214, vcc
	v_lshlrev_b32_e32 v16, 2, v0
	v_lshlrev_b32_e32 v0, 5, v208
	v_lshl_or_b32 v6, v17, 4, v6
	v_readlane_b32 s1, v254, 1
	v_lshlrev_b64 v[8:9], 13, v[8:9]
	v_and_b32_e32 v4, 0x7e0, v0
	v_mov_b32_e32 v5, 0
	v_lshl_add_u64 v[6:7], s[0:1], 0, v[6:7]
	s_mov_b64 s[0:1], 0x8578800
	v_lshl_or_b32 v8, v17, 5, v8
	s_waitcnt lgkmcnt(0)
	v_lshl_add_u64 v[0:1], s[2:3], 0, v[4:5]
	v_or_b32_e32 v2, 0x1000, v4
	v_mov_b32_e32 v3, v5
	v_or_b32_e32 v4, 0x1800, v4
	v_lshl_add_u64 v[6:7], v[6:7], 0, s[0:1]
	v_lshl_add_u64 v[8:9], s[6:7], 0, v[8:9]
	s_mov_b64 s[0:1], 0x1000
	v_lshl_add_u64 v[2:3], s[2:3], 0, v[2:3]
	v_lshl_add_u64 v[4:5], s[2:3], 0, v[4:5]
	v_lshl_add_u64 v[8:9], v[8:9], 0, s[0:1]
	s_mov_b64 s[0:1], 0
	v_mov_b32_e32 v17, 0x358637bd
	s_mov_b32 s2, 0x800000
	s_movk_i32 s3, 0x3fff
	global_load_dwordx4 v[160:163], v[0:1], off
	global_load_dwordx4 v[164:167], v[0:1], off offset:16
	global_load_dwordx4 v[168:171], v[0:1], off offset:2048
	global_load_dwordx4 v[172:175], v[0:1], off offset:2064
	global_load_dwordx4 v[176:179], v[2:3], off
	global_load_dwordx4 v[180:183], v[2:3], off offset:16
	global_load_dwordx4 v[184:187], v[4:5], off
	global_load_dwordx4 v[188:191], v[4:5], off offset:16
.LBB0_1054:
	global_load_dwordx4 v[18:21], v[6:7], off offset:-2048
	global_load_dwordx4 v[22:25], v[6:7], off offset:-1024
	global_load_dwordx4 v[26:29], v[6:7], off
	global_load_dwordx4 v[30:33], v[6:7], off offset:1024
	v_add_u32_e32 v10, s96, v10
	v_lshl_add_u64 v[6:7], v[6:7], 0, s[10:11]
	s_waitcnt vmcnt(3)
	v_lshlrev_b32_e32 v38, 16, v18
	v_and_b32_e32 v39, 0xffff0000, v18
	v_lshlrev_b32_e32 v18, 16, v19
	v_and_b32_e32 v19, 0xffff0000, v19
	v_lshlrev_b32_e32 v40, 16, v20
	v_and_b32_e32 v41, 0xffff0000, v20
	v_lshlrev_b32_e32 v42, 16, v21
	v_and_b32_e32 v43, 0xffff0000, v21
	v_pk_mul_f32 v[20:21], v[38:39], v[38:39]
	v_pk_mul_f32 v[56:57], v[18:19], v[18:19]
	v_add_f32_e32 v20, v20, v21
	v_add_f32_e32 v20, v56, v20
	v_pk_mul_f32 v[58:59], v[40:41], v[40:41]
	v_add_f32_e32 v20, v57, v20
	v_add_f32_e32 v20, v58, v20
	v_pk_mul_f32 v[60:61], v[42:43], v[42:43]
	v_add_f32_e32 v20, v59, v20
	s_waitcnt vmcnt(2)
	v_lshlrev_b32_e32 v44, 16, v22
	v_and_b32_e32 v45, 0xffff0000, v22
	v_add_f32_e32 v20, v60, v20
	v_pk_mul_f32 v[62:63], v[44:45], v[44:45]
	v_add_f32_e32 v20, v61, v20
	v_lshlrev_b32_e32 v22, 16, v23
	v_and_b32_e32 v23, 0xffff0000, v23
	v_add_f32_e32 v20, v62, v20
	v_pk_mul_f32 v[64:65], v[22:23], v[22:23]
	v_add_f32_e32 v20, v63, v20
	v_lshlrev_b32_e32 v46, 16, v24
	v_and_b32_e32 v47, 0xffff0000, v24
	v_add_f32_e32 v20, v64, v20
	v_pk_mul_f32 v[66:67], v[46:47], v[46:47]
	v_add_f32_e32 v20, v65, v20
	v_lshlrev_b32_e32 v24, 16, v25
	v_and_b32_e32 v25, 0xffff0000, v25
	v_add_f32_e32 v20, v66, v20
	v_pk_mul_f32 v[68:69], v[24:25], v[24:25]
	v_add_f32_e32 v20, v67, v20
	s_waitcnt vmcnt(1)
	v_lshlrev_b32_e32 v48, 16, v26
	v_and_b32_e32 v49, 0xffff0000, v26
	v_add_f32_e32 v20, v68, v20
	v_pk_mul_f32 v[70:71], v[48:49], v[48:49]
	v_add_f32_e32 v20, v69, v20
	v_lshlrev_b32_e32 v26, 16, v27
	v_and_b32_e32 v27, 0xffff0000, v27
	v_add_f32_e32 v20, v70, v20
	v_pk_mul_f32 v[72:73], v[26:27], v[26:27]
	v_add_f32_e32 v20, v71, v20
	v_lshlrev_b32_e32 v50, 16, v28
	v_and_b32_e32 v51, 0xffff0000, v28
	v_add_f32_e32 v20, v72, v20
	v_pk_mul_f32 v[74:75], v[50:51], v[50:51]
	v_add_f32_e32 v20, v73, v20
	v_lshlrev_b32_e32 v28, 16, v29
	v_and_b32_e32 v29, 0xffff0000, v29
	v_add_f32_e32 v20, v74, v20
	v_pk_mul_f32 v[76:77], v[28:29], v[28:29]
	v_add_f32_e32 v20, v75, v20
	s_waitcnt vmcnt(0)
	v_lshlrev_b32_e32 v52, 16, v30
	v_and_b32_e32 v53, 0xffff0000, v30
	v_add_f32_e32 v20, v76, v20
	v_pk_mul_f32 v[78:79], v[52:53], v[52:53]
	v_add_f32_e32 v20, v77, v20
	v_lshlrev_b32_e32 v30, 16, v31
	v_and_b32_e32 v31, 0xffff0000, v31
	v_add_f32_e32 v20, v78, v20
	v_pk_mul_f32 v[80:81], v[30:31], v[30:31]
	v_add_f32_e32 v20, v79, v20
	v_lshlrev_b32_e32 v54, 16, v32
	v_and_b32_e32 v55, 0xffff0000, v32
	v_add_f32_e32 v20, v80, v20
	v_pk_mul_f32 v[82:83], v[54:55], v[54:55]
	v_add_f32_e32 v20, v81, v20
	v_lshlrev_b32_e32 v32, 16, v33
	v_and_b32_e32 v33, 0xffff0000, v33
	v_add_f32_e32 v20, v82, v20
	v_pk_mul_f32 v[84:85], v[32:33], v[32:33]
	v_add_f32_e32 v20, v83, v20
	v_add_f32_e32 v20, v84, v20
	v_add_f32_e32 v20, v85, v20
	ds_bpermute_b32 v21, v11, v20
	s_waitcnt lgkmcnt(0)
	v_add_f32_e32 v20, v20, v21
	ds_bpermute_b32 v21, v12, v20
	s_waitcnt lgkmcnt(0)
	v_add_f32_e32 v20, v20, v21
	ds_bpermute_b32 v21, v13, v20
	s_waitcnt lgkmcnt(0)
	v_add_f32_e32 v20, v20, v21
	ds_bpermute_b32 v21, v14, v20
	s_waitcnt lgkmcnt(0)
	v_add_f32_e32 v20, v20, v21
	ds_bpermute_b32 v21, v15, v20
	s_waitcnt lgkmcnt(0)
	v_add_f32_e32 v20, v20, v21
	ds_bpermute_b32 v21, v16, v20
	s_waitcnt lgkmcnt(0)
	v_add_f32_e32 v20, v20, v21
	v_fmamk_f32 v20, v20, 0x3a000000, v17
	v_mul_f32_e32 v21, 0x4b800000, v20
	v_cmp_gt_f32_e32 vcc, s2, v20
	s_nop 1
	v_cndmask_b32_e32 v20, v20, v21, vcc
	v_rsq_f32_e32 v20, v20
	s_nop 0
	v_mul_f32_e32 v21, 0x45800000, v20
	v_cndmask_b32_e32 v56, v20, v21, vcc
	v_pk_mul_f32 v[38:39], v[56:57], v[38:39] op_sel_hi:[0,1]
	v_pk_mul_f32 v[18:19], v[56:57], v[18:19] op_sel_hi:[0,1]
	s_waitcnt vmcnt(0)
	v_pk_mul_f32 v[20:21], v[162:163], v[18:19]
	v_pk_mul_f32 v[18:19], v[160:161], v[38:39]
	global_store_dwordx4 v[8:9], v[18:21], off offset:-4096
	s_nop 1
	v_pk_mul_f32 v[34:35], v[56:57], v[42:43] op_sel_hi:[0,1]
	v_pk_mul_f32 v[36:37], v[56:57], v[40:41] op_sel_hi:[0,1]
	v_pk_mul_f32 v[22:23], v[56:57], v[22:23] op_sel_hi:[0,1]
	v_cmp_lt_i32_e32 vcc, s3, v10
	s_or_b64 s[0:1], vcc, s[0:1]
	v_pk_mul_f32 v[18:19], v[164:165], v[36:37]
	v_pk_mul_f32 v[20:21], v[166:167], v[34:35]
	global_store_dwordx4 v[8:9], v[18:21], off offset:-4080
	s_nop 1
	v_pk_mul_f32 v[34:35], v[56:57], v[44:45] op_sel_hi:[0,1]
	v_pk_mul_f32 v[18:19], v[168:169], v[34:35]
	v_pk_mul_f32 v[20:21], v[170:171], v[22:23]
	global_store_dwordx4 v[8:9], v[18:21], off offset:-2048
	s_nop 1
	v_pk_mul_f32 v[22:23], v[56:57], v[24:25] op_sel_hi:[0,1]
	v_pk_mul_f32 v[24:25], v[56:57], v[46:47] op_sel_hi:[0,1]
	v_pk_mul_f32 v[18:19], v[172:173], v[24:25]
	v_pk_mul_f32 v[20:21], v[174:175], v[22:23]
	global_store_dwordx4 v[8:9], v[18:21], off offset:-2032
	s_nop 1
	v_pk_mul_f32 v[22:23], v[56:57], v[26:27] op_sel_hi:[0,1]
	v_pk_mul_f32 v[24:25], v[56:57], v[48:49] op_sel_hi:[0,1]
	v_pk_mul_f32 v[18:19], v[176:177], v[24:25]
	v_pk_mul_f32 v[20:21], v[178:179], v[22:23]
	global_store_dwordx4 v[8:9], v[18:21], off
	s_nop 1
	v_pk_mul_f32 v[22:23], v[56:57], v[28:29] op_sel_hi:[0,1]
	v_pk_mul_f32 v[24:25], v[56:57], v[50:51] op_sel_hi:[0,1]
	v_pk_mul_f32 v[18:19], v[180:181], v[24:25]
	v_pk_mul_f32 v[20:21], v[182:183], v[22:23]
	global_store_dwordx4 v[8:9], v[18:21], off offset:16
	s_nop 1
	v_pk_mul_f32 v[22:23], v[56:57], v[30:31] op_sel_hi:[0,1]
	v_pk_mul_f32 v[24:25], v[56:57], v[52:53] op_sel_hi:[0,1]
	v_pk_mul_f32 v[18:19], v[184:185], v[24:25]
	v_pk_mul_f32 v[20:21], v[186:187], v[22:23]
	global_store_dwordx4 v[8:9], v[18:21], off offset:2048
	s_nop 1
	v_pk_mul_f32 v[22:23], v[56:57], v[32:33] op_sel_hi:[0,1]
	v_pk_mul_f32 v[24:25], v[56:57], v[54:55] op_sel_hi:[0,1]
	v_pk_mul_f32 v[18:19], v[188:189], v[24:25]
	v_pk_mul_f32 v[20:21], v[190:191], v[22:23]
	global_store_dwordx4 v[8:9], v[18:21], off offset:2064
	s_nop 1
	v_lshl_add_u64 v[8:9], v[8:9], 0, s[12:13]
	s_andn2_b64 exec, exec, s[0:1]
	s_cbranch_execnz .LBB0_1054
